# combo8 + final RMSNorm loop: second-half x/g loads issued with the first batch (one memory round trip per row instead of two)
# baseline (speedup 1.0000x reference)
.LBB0_46:
	s_add_u32 s20, s78, s6
	v_lshl_add_u64 v[14:15], s[78:79], 0, v[6:7]
	s_mov_b32 s15, 0x3000000
	s_addc_u32 s21, s79, s7
	v_add_co_u32_e32 v38, vcc, s15, v14
	v_mov_b32_e32 v0, 0x1f800000
	global_load_dwordx4 v[10:13], v[2:3], off
	v_addc_co_u32_e32 v39, vcc, 0, v15, vcc
	global_load_dwordx4 v[14:17], v0, s[20:21]
	global_load_dwordx4 v[18:21], v[38:39], off
	s_add_u32 s20, s20, 0x1f800000
	s_addc_u32 s21, s21, 0
	global_load_dwordx4 v[22:25], v1, s[20:21] offset:16
	global_load_dwordx4 v[26:29], v1, s[20:21] offset:32
	global_load_dwordx4 v[30:33], v1, s[20:21] offset:48
	global_load_dwordx4 v[34:37], v[2:3], off offset:16
	global_load_dwordx4 v[44:47], v[38:39], off offset:1024
	global_load_dwordx4 v[48:51], v[4:5], off
	global_load_dwordx4 v[52:55], v[4:5], off offset:16
	s_add_i32 s11, s11, s10
	s_add_u32 s6, s6, s8
	s_addc_u32 s7, s7, s9
	v_lshl_add_u64 v[6:7], v[6:7], 0, s[16:17]
	s_cmp_gt_i32 s11, 0xbfff
	s_waitcnt vmcnt(0)
	v_mov_b32_e32 v40, v15
	v_mov_b32_e32 v41, v16
	v_mov_b32_e32 v15, v17
	v_pk_add_f32 v[14:15], v[40:41], v[14:15]
	s_waitcnt vmcnt(3)
	v_mov_b32_e32 v40, v23
	v_mov_b32_e32 v41, v24
	v_mov_b32_e32 v23, v25
	v_pk_add_f32 v[22:23], v[40:41], v[22:23]
	v_pk_add_f32 v[14:15], v[14:15], v[14:15] op_sel:[0,1] op_sel_hi:[1,0]
	v_pk_add_f32 v[22:23], v[22:23], v[22:23] op_sel:[0,1] op_sel_hi:[1,0]
	s_waitcnt vmcnt(2)
	v_add_f32_e32 v24, v26, v27
	v_add_f32_e32 v26, v28, v29
	s_waitcnt vmcnt(1)
	v_mov_b32_e32 v25, v32
	v_mov_b32_e32 v27, v33
	v_mov_b32_e32 v15, v30
	v_mov_b32_e32 v23, v31
	v_pk_add_f32 v[24:25], v[24:25], v[26:27]
	v_pk_add_f32 v[14:15], v[14:15], v[22:23]
	v_lshlrev_b32_e32 v16, 16, v18
	v_pk_add_f32 v[14:15], v[14:15], v[24:25]
	v_and_b32_e32 v17, 0xffff0000, v18
	v_add_f32_e32 v0, v14, v15
	v_fmamk_f32 v0, v0, 0x3a800000, v223
	v_rsq_f32_e32 v0, v0
	v_lshlrev_b32_e32 v18, 16, v19
	v_and_b32_e32 v19, 0xffff0000, v19
	v_lshlrev_b32_e32 v42, 16, v20
	v_and_b32_e32 v43, 0xffff0000, v20
	v_lshlrev_b32_e32 v20, 16, v21
	v_and_b32_e32 v21, 0xffff0000, v21
	v_pk_mul_f32 v[14:15], v[0:1], v[16:17] op_sel_hi:[0,1]
	v_pk_mul_f32 v[16:17], v[0:1], v[18:19] op_sel_hi:[0,1]
	v_pk_mul_f32 v[18:19], v[0:1], v[42:43] op_sel_hi:[0,1]
	v_pk_mul_f32 v[20:21], v[0:1], v[20:21] op_sel_hi:[0,1]
	v_pk_mul_f32 v[12:13], v[12:13], v[16:17]
	v_pk_mul_f32 v[10:11], v[10:11], v[14:15]
	s_waitcnt vmcnt(0)
	v_pk_mul_f32 v[16:17], v[36:37], v[20:21]
	v_pk_mul_f32 v[14:15], v[34:35], v[18:19]
	global_store_dwordx4 v[8:9], v[10:13], off offset:-2064 nt
	global_store_dwordx4 v[8:9], v[14:17], off offset:-2048 nt
	v_lshlrev_b32_e32 v22, 16, v44
	v_and_b32_e32 v23, 0xffff0000, v44
	v_lshlrev_b32_e32 v10, 16, v45
	v_and_b32_e32 v11, 0xffff0000, v45
	v_lshlrev_b32_e32 v24, 16, v46
	v_and_b32_e32 v25, 0xffff0000, v46
	v_lshlrev_b32_e32 v12, 16, v47
	v_and_b32_e32 v13, 0xffff0000, v47
	v_pk_mul_f32 v[22:23], v[0:1], v[22:23] op_sel_hi:[0,1]
	v_pk_mul_f32 v[10:11], v[0:1], v[10:11] op_sel_hi:[0,1]
	v_pk_mul_f32 v[24:25], v[0:1], v[24:25] op_sel_hi:[0,1]
	v_pk_mul_f32 v[26:27], v[0:1], v[12:13] op_sel_hi:[0,1]
	v_pk_mul_f32 v[12:13], v[50:51], v[10:11]
	v_pk_mul_f32 v[10:11], v[48:49], v[22:23]
	v_pk_mul_f32 v[16:17], v[54:55], v[26:27]
	v_pk_mul_f32 v[14:15], v[52:53], v[24:25]
	global_store_dwordx4 v[8:9], v[10:13], off offset:-16 nt
	global_store_dwordx4 v[8:9], v[14:17], off nt
	v_lshl_add_u64 v[8:9], v[8:9], 0, s[18:19]
	s_cbranch_scc0 .LBB0_46
